# GU epilogue: lane pairs exchanged with v_permlane16_swap so ACT is written with 16-byte stores (half the store instructions); on top of merged phases
# speedup vs baseline: 1.0277x; 1.0155x over previous
; DI unsigned pk2(float lo, float hi) { const f32x2 v = {lo, hi}; return __builtin_bit_cast(unsigned, __builtin_convertvector(v, bf2_t)); }
; #define BAR() { __builtin_amdgcn_sched_barrier(0); __builtin_amdgcn_s_barrier(); asm volatile("" ::: "memory"); __builtin_amdgcn_sched_barrier(0); }
; DI void gemm_stream2(const bf16_t* __restrict__ A, int lda, const bf16_t* __restrict__ Bt, int ldb, int K, int m0, int n0, ...
;     ...
;     const int wave = __builtin_amdgcn_readfirstlane(tid >> 6), lane = tid & 63, wm = wave >> 1, wn = wave & 1, r = lane & 15, q = lane >> 4;
;     const int sc0 = ((lane & 7) ^ (lane >> 4)) * 8, sc1 = ((lane & 7) ^ (4 | (lane >> 4))) * 8;
;     const bf16_t* ga = A + (size_t)(m0 + wave * 32 + (lane >> 3)) * lda;
;     const bf16_t* gb = Bt + (size_t)(n0 + wave * 16 + (lane >> 3)) * ldb;
;     const bf16_t* gan = An + (size_t)(m0n + wave * 32 + (lane >> 3)) * ldan;
;     const bf16_t* gbn = Btn + (size_t)(n0n + wave * 16 + (lane >> 3)) * ldbn;
;     const unsigned wa = (unsigned)wave * 4096u, wbb = 32768u + (unsigned)wave * 2048u;
;     ...
;     const int sw = r >> 1;
;     const unsigned fo0 = (unsigned)(r * 128 + ((q ^ sw) << 4)), fo1 = (unsigned)(r * 128 + (((q ^ sw) ^ 4) << 4));
;     const unsigned aoff = (unsigned)(wm * 64) * 128u, boff = 32768u + (unsigned)(wn * 64) * 128u;
;     const int nk = K / 64;
;     const int grp = wave >> 2;
;     ...
;     int st = rg.st;
;     if (!rg.primed) {
;         const int s1p = st == 2 ? 0 : st + 1;
;         BAR();
;         STAGE(st, 0);
;         STAGE(s1p, 1);
;         asm volatile("s_waitcnt vmcnt(6)" ::: "memory");
;         BAR();
;     }
;     if (grp == 1) BAR();
; DI void gemm_gu(const Params& p, size_t woff, int bid, int nb, char* smem, const int tid) {
;     ...
;             const int row = m0 + wm * 64 + mi * 16 + r;
; #pragma unroll
;             for (int pr = 0; pr < 2; ++pr) {
;                 const f32x4 g = acc[mi][2 * pr], u = acc[mi][2 * pr + 1];
;                 float o[4];
; #pragma unroll
;                 for (int j = 0; j < 4; ++j) o[j] = g[j] * __builtin_amdgcn_rcpf(1.0f + __builtin_amdgcn_exp2f(-LOG2E * g[j])) * u[j];
;                 const int col = ((nb0 + pr * 32) >> 5) * 16 + q * 4;
;                 u32x2 w; w.x = pk2(o[0], o[1]); w.y = pk2(o[2], o[3]);
;                 *(u32x2*)(ACT + (size_t)row * DFF + col) = w;
.Lgu_ranged:
	s_cmp_ge_u32 s51, s52
	s_cbranch_scc1 .LBB0_860
	v_and_b32_e32 v190, 63, v193
	v_and_b32_e32 v191, 15, v190
	v_lshrrev_b32_e32 v17, 4, v190
	v_lshrrev_b32_e32 v18, 3, v190
	v_and_b32_e32 v19, 7, v190
	v_xor_b32_e32 v195, v19, v17
	v_lshlrev_b32_e32 v195, 4, v195
	v_lshl_add_u32 v184, v18, 11, v195
	v_or_b32_e32 v195, 4, v17
	v_xor_b32_e32 v195, v19, v195
	v_lshlrev_b32_e32 v195, 4, v195
	v_add_u32_e32 v227, 8, v18
	v_lshl_add_u32 v185, v227, 11, v195
	v_lshrrev_b32_e32 v195, 1, v191
	v_xor_b32_e32 v195, v17, v195
	v_lshlrev_b32_e32 v195, 4, v195
	s_lshl_b32 s1, s33, 6
	v_add_u32_e32 v227, s1, v191
	v_lshl_add_u32 v186, v227, 7, v195
	v_xor_b32_e32 v187, 64, v186
	v_mul_u32_u24_e32 v228, 0x1600, v227
	s_lshl_b32 s1, s36, 5
	v_add_u32_e32 v227, s1, v191
	v_lshl_add_u32 v188, v227, 7, v195
	v_add_u32_e32 v188, 0x10000, v188
	v_xor_b32_e32 v189, 64, v188
	v_lshl_add_u32 v229, v17, 3, s1
	v_add_u32_e32 v237, v228, v229
	v_and_b32_e32 v227, 1, v17
	v_mul_u32_u24_e32 v227, 0x15ff8, v227
	v_add_u32_e32 v237, v237, v227
	s_mul_i32 s1, s51, 0x1745e
	s_lshr_b32 s2, s1, 24
	s_mul_i32 s1, s2, 0xb0
	s_sub_u32 s1, s51, s1
	s_lshr_b32 s3, s1, 3
	s_and_b32 s37, s1, 7
	s_cmp_lt_u32 s2, 8
	s_cselect_b32 s58, s3, s1
	s_cselect_b32 s37, s37, 0
	s_lshl_b32 s2, s2, 3
	s_add_i32 s57, s2, s37
	s_lshl_b32 s1, s57, 19
	s_lshl_b32 s2, s10, 15
	s_add_u32 s1, s1, s2
	s_add_u32 s1, s1, 0x3240000
	s_add_u32 s66, s88, s1
	s_addc_u32 s67, s89, 0
	s_add_u32 s68, s66, 0x40000
	s_addc_u32 s69, s67, 0
	s_lshl_b32 s1, s58, 19
	s_add_u32 s1, s1, s2
	s_add_u32 s1, s1, s61
	s_add_u32 s70, s88, s1
	s_addc_u32 s71, s89, 0
	s_add_u32 s72, s70, 0x40000
	s_addc_u32 s73, s71, 0
	s_add_i32 m0, s39, 0x10000
	s_nop 0
	global_load_lds_dwordx4 v184, s[70:71]
	s_add_i32 m0, s39, 0x10400
	s_nop 0
	global_load_lds_dwordx4 v185, s[70:71]
	s_add_u32 s70, s70, 0x80
	s_addc_u32 s71, s71, 0
	s_add_i32 m0, s39, 0x0
	s_nop 0
	global_load_lds_dwordx4 v184, s[66:67]
	s_add_i32 m0, s39, 0x400
	s_nop 0
	global_load_lds_dwordx4 v185, s[66:67]
	s_add_u32 s66, s66, 0x80
	s_addc_u32 s67, s67, 0
	s_add_i32 m0, s39, 0x14000
	s_nop 0
	global_load_lds_dwordx4 v184, s[72:73]
	s_add_i32 m0, s39, 0x14400
	s_nop 0
	global_load_lds_dwordx4 v185, s[72:73]
	s_add_u32 s72, s72, 0x80
	s_addc_u32 s73, s73, 0
	s_add_i32 m0, s39, 0x4000
	s_nop 0
	global_load_lds_dwordx4 v184, s[68:69]
	s_add_i32 m0, s39, 0x4400
	s_nop 0
	global_load_lds_dwordx4 v185, s[68:69]
	s_add_u32 s68, s68, 0x80
	s_addc_u32 s69, s69, 0
	s_add_i32 m0, s39, 0x18000
	s_nop 0
	global_load_lds_dwordx4 v184, s[70:71]
	s_add_i32 m0, s39, 0x18400
	s_nop 0
	global_load_lds_dwordx4 v185, s[70:71]
	s_add_u32 s70, s70, 0x80
	s_addc_u32 s71, s71, 0
	s_add_i32 m0, s39, 0x8000
	s_nop 0
	global_load_lds_dwordx4 v184, s[66:67]
	s_add_i32 m0, s39, 0x8400
	s_nop 0
	global_load_lds_dwordx4 v185, s[66:67]
	s_add_u32 s66, s66, 0x80
	s_addc_u32 s67, s67, 0
	s_add_i32 m0, s39, 0x1c000
	s_nop 0
	global_load_lds_dwordx4 v184, s[72:73]
	s_add_i32 m0, s39, 0x1c400
	s_nop 0
	global_load_lds_dwordx4 v185, s[72:73]
	s_add_u32 s72, s72, 0x80
	s_addc_u32 s73, s73, 0
	s_waitcnt vmcnt(8)
	s_barrier
	s_cmp_eq_u32 s33, 0
	s_cbranch_scc1 .Lgu_lead
	s_barrier

; DI unsigned pk2(float lo, float hi) { const f32x2 v = {lo, hi}; return __builtin_bit_cast(unsigned, __builtin_convertvector(v, bf2_t)); }
; DI void gemm_gu(const Params& p, size_t woff, int bid, int nb, char* smem, const int tid) {
;     ...
;         const int nb0 = n0 + wn * 64;
; #pragma unroll
;         for (int mi = 0; mi < 4; ++mi) {
;             const int row = m0 + wm * 64 + mi * 16 + r;
; #pragma unroll
;             for (int pr = 0; pr < 2; ++pr) {
;                 const f32x4 g = acc[mi][2 * pr], u = acc[mi][2 * pr + 1];
;                 float o[4];
; #pragma unroll
;                 for (int j = 0; j < 4; ++j) o[j] = g[j] * __builtin_amdgcn_rcpf(1.0f + __builtin_amdgcn_exp2f(-LOG2E * g[j])) * u[j];
;                 const int col = ((nb0 + pr * 32) >> 5) * 16 + q * 4;
;                 u32x2 w; w.x = pk2(o[0], o[1]); w.y = pk2(o[2], o[3]);
;                 *(u32x2*)(ACT + (size_t)row * DFF + col) = w;
;             }
;         }
.Lgu_epi:
	s_mul_i32 s1, s57, 0x160000
	s_lshl_b32 s62, s58, 8
	s_add_u32 s1, s1, s62
	s_add_u32 s1, s1, 0x52c0000
	s_add_u32 s2, s88, s1
	s_addc_u32 s3, s89, 0
	s_nop 7
	s_nop 7
	v_mul_f32_e32 v152, 0xbfb8aa3b, v24
	v_mul_f32_e32 v153, 0xbfb8aa3b, v25
	v_mul_f32_e32 v154, 0xbfb8aa3b, v26
	v_mul_f32_e32 v155, 0xbfb8aa3b, v27
	v_exp_f32_e32 v152, v152
	v_exp_f32_e32 v153, v153
	v_exp_f32_e32 v154, v154
	v_exp_f32_e32 v155, v155
	s_nop 0
	v_add_f32_e32 v152, 1.0, v152
	v_add_f32_e32 v153, 1.0, v153
	v_add_f32_e32 v154, 1.0, v154
	v_add_f32_e32 v155, 1.0, v155
	v_rcp_f32_e32 v152, v152
	v_rcp_f32_e32 v153, v153
	v_rcp_f32_e32 v154, v154
	v_rcp_f32_e32 v155, v155
	s_nop 0
	v_pk_mul_f32 v[152:153], v[24:25], v[152:153]
	v_pk_mul_f32 v[154:155], v[26:27], v[154:155]
	v_pk_mul_f32 v[152:153], v[28:29], v[152:153]
	v_pk_mul_f32 v[154:155], v[30:31], v[154:155]
	v_cvt_pk_bf16_f32 v152, v152, v153
	v_cvt_pk_bf16_f32 v153, v154, v155
	v_mul_f32_e32 v156, 0xbfb8aa3b, v32
	v_mul_f32_e32 v157, 0xbfb8aa3b, v33
	v_mul_f32_e32 v158, 0xbfb8aa3b, v34
	v_mul_f32_e32 v159, 0xbfb8aa3b, v35
	v_exp_f32_e32 v156, v156
	v_exp_f32_e32 v157, v157
	v_exp_f32_e32 v158, v158
	v_exp_f32_e32 v159, v159
	s_nop 0
	v_add_f32_e32 v156, 1.0, v156
	v_add_f32_e32 v157, 1.0, v157
	v_add_f32_e32 v158, 1.0, v158
	v_add_f32_e32 v159, 1.0, v159
	v_rcp_f32_e32 v156, v156
	v_rcp_f32_e32 v157, v157
	v_rcp_f32_e32 v158, v158
	v_rcp_f32_e32 v159, v159
	s_nop 0
	v_pk_mul_f32 v[156:157], v[32:33], v[156:157]
	v_pk_mul_f32 v[158:159], v[34:35], v[158:159]
	v_pk_mul_f32 v[156:157], v[36:37], v[156:157]
	v_pk_mul_f32 v[158:159], v[38:39], v[158:159]
	v_cvt_pk_bf16_f32 v154, v156, v157
	v_cvt_pk_bf16_f32 v155, v158, v159
	s_nop 1
	v_permlane16_swap_b32_e32 v152, v154
	v_permlane16_swap_b32_e32 v153, v155
	global_store_dwordx4 v237, v[152:155], s[2:3] offset:0
	v_mul_f32_e32 v160, 0xbfb8aa3b, v56
	v_mul_f32_e32 v161, 0xbfb8aa3b, v57
	v_mul_f32_e32 v162, 0xbfb8aa3b, v58
	v_mul_f32_e32 v163, 0xbfb8aa3b, v59
	v_exp_f32_e32 v160, v160
	v_exp_f32_e32 v161, v161
	v_exp_f32_e32 v162, v162
	v_exp_f32_e32 v163, v163
	s_nop 0
	v_add_f32_e32 v160, 1.0, v160
	v_add_f32_e32 v161, 1.0, v161
	v_add_f32_e32 v162, 1.0, v162
	v_add_f32_e32 v163, 1.0, v163
	v_rcp_f32_e32 v160, v160
	v_rcp_f32_e32 v161, v161
	v_rcp_f32_e32 v162, v162
	v_rcp_f32_e32 v163, v163
	s_nop 0
	v_pk_mul_f32 v[160:161], v[56:57], v[160:161]
	v_pk_mul_f32 v[162:163], v[58:59], v[162:163]
	v_pk_mul_f32 v[160:161], v[60:61], v[160:161]
	v_pk_mul_f32 v[162:163], v[62:63], v[162:163]
	v_cvt_pk_bf16_f32 v160, v160, v161
	v_cvt_pk_bf16_f32 v161, v162, v163
	v_mul_f32_e32 v164, 0xbfb8aa3b, v64
	v_mul_f32_e32 v165, 0xbfb8aa3b, v65
	v_mul_f32_e32 v166, 0xbfb8aa3b, v66
	v_mul_f32_e32 v167, 0xbfb8aa3b, v67
	v_exp_f32_e32 v164, v164
	v_exp_f32_e32 v165, v165
	v_exp_f32_e32 v166, v166
	v_exp_f32_e32 v167, v167
	s_nop 0
	v_add_f32_e32 v164, 1.0, v164
	v_add_f32_e32 v165, 1.0, v165
	v_add_f32_e32 v166, 1.0, v166
	v_add_f32_e32 v167, 1.0, v167
	v_rcp_f32_e32 v164, v164
	v_rcp_f32_e32 v165, v165
	v_rcp_f32_e32 v166, v166
	v_rcp_f32_e32 v167, v167
	s_nop 0
	v_pk_mul_f32 v[164:165], v[64:65], v[164:165]
	v_pk_mul_f32 v[166:167], v[66:67], v[166:167]
	v_pk_mul_f32 v[164:165], v[68:69], v[164:165]
	v_pk_mul_f32 v[166:167], v[70:71], v[166:167]
	v_cvt_pk_bf16_f32 v162, v164, v165
	v_cvt_pk_bf16_f32 v163, v166, v167
	s_nop 1
	v_permlane16_swap_b32_e32 v160, v162
	v_permlane16_swap_b32_e32 v161, v163
	global_store_dwordx4 v237, v[160:163], s[2:3] offset:128
	s_add_u32 s2, s2, 0x2c000
	s_addc_u32 s3, s3, 0
	v_mul_f32_e32 v168, 0xbfb8aa3b, v40
	v_mul_f32_e32 v169, 0xbfb8aa3b, v41
	v_mul_f32_e32 v170, 0xbfb8aa3b, v42
	v_mul_f32_e32 v171, 0xbfb8aa3b, v43
	v_exp_f32_e32 v168, v168
	v_exp_f32_e32 v169, v169
	v_exp_f32_e32 v170, v170
	v_exp_f32_e32 v171, v171
	s_nop 0
	v_add_f32_e32 v168, 1.0, v168
	v_add_f32_e32 v169, 1.0, v169
	v_add_f32_e32 v170, 1.0, v170
	v_add_f32_e32 v171, 1.0, v171
	v_rcp_f32_e32 v168, v168
	v_rcp_f32_e32 v169, v169
	v_rcp_f32_e32 v170, v170
	v_rcp_f32_e32 v171, v171
	s_nop 0
	v_pk_mul_f32 v[168:169], v[40:41], v[168:169]
	v_pk_mul_f32 v[170:171], v[42:43], v[170:171]
	v_pk_mul_f32 v[168:169], v[44:45], v[168:169]
	v_pk_mul_f32 v[170:171], v[46:47], v[170:171]
	v_cvt_pk_bf16_f32 v168, v168, v169
	v_cvt_pk_bf16_f32 v169, v170, v171
	v_mul_f32_e32 v172, 0xbfb8aa3b, v48
	v_mul_f32_e32 v173, 0xbfb8aa3b, v49
	v_mul_f32_e32 v174, 0xbfb8aa3b, v50
	v_mul_f32_e32 v175, 0xbfb8aa3b, v51
	v_exp_f32_e32 v172, v172
	v_exp_f32_e32 v173, v173
	v_exp_f32_e32 v174, v174
	v_exp_f32_e32 v175, v175
	s_nop 0
	v_add_f32_e32 v172, 1.0, v172
	v_add_f32_e32 v173, 1.0, v173
	v_add_f32_e32 v174, 1.0, v174
	v_add_f32_e32 v175, 1.0, v175
	v_rcp_f32_e32 v172, v172
	v_rcp_f32_e32 v173, v173
	v_rcp_f32_e32 v174, v174
	v_rcp_f32_e32 v175, v175
	s_nop 0
	v_pk_mul_f32 v[172:173], v[48:49], v[172:173]
	v_pk_mul_f32 v[174:175], v[50:51], v[174:175]
	v_pk_mul_f32 v[172:173], v[52:53], v[172:173]
	v_pk_mul_f32 v[174:175], v[54:55], v[174:175]
	v_cvt_pk_bf16_f32 v170, v172, v173
	v_cvt_pk_bf16_f32 v171, v174, v175
	s_nop 1
	v_permlane16_swap_b32_e32 v168, v170
	v_permlane16_swap_b32_e32 v169, v171
	global_store_dwordx4 v237, v[168:171], s[2:3] offset:0
	v_mul_f32_e32 v152, 0xbfb8aa3b, v72
	v_mul_f32_e32 v153, 0xbfb8aa3b, v73
	v_mul_f32_e32 v154, 0xbfb8aa3b, v74
	v_mul_f32_e32 v155, 0xbfb8aa3b, v75
	v_exp_f32_e32 v152, v152
	v_exp_f32_e32 v153, v153
	v_exp_f32_e32 v154, v154
	v_exp_f32_e32 v155, v155
	s_nop 0
	v_add_f32_e32 v152, 1.0, v152
	v_add_f32_e32 v153, 1.0, v153
	v_add_f32_e32 v154, 1.0, v154
	v_add_f32_e32 v155, 1.0, v155
	v_rcp_f32_e32 v152, v152
	v_rcp_f32_e32 v153, v153
; DI unsigned pk2(float lo, float hi) { const f32x2 v = {lo, hi}; return __builtin_bit_cast(unsigned, __builtin_convertvector(v, bf2_t)); }
; DI void gemm_gu(const Params& p, size_t woff, int bid, int nb, char* smem, const int tid) {
;     ...
;         const int nb0 = n0 + wn * 64;
; #pragma unroll
;         for (int mi = 0; mi < 4; ++mi) {
;             const int row = m0 + wm * 64 + mi * 16 + r;
; #pragma unroll
;             for (int pr = 0; pr < 2; ++pr) {
;                 const f32x4 g = acc[mi][2 * pr], u = acc[mi][2 * pr + 1];
;                 float o[4];
; #pragma unroll
;                 for (int j = 0; j < 4; ++j) o[j] = g[j] * __builtin_amdgcn_rcpf(1.0f + __builtin_amdgcn_exp2f(-LOG2E * g[j])) * u[j];
;                 const int col = ((nb0 + pr * 32) >> 5) * 16 + q * 4;
;                 u32x2 w; w.x = pk2(o[0], o[1]); w.y = pk2(o[2], o[3]);
;                 *(u32x2*)(ACT + (size_t)row * DFF + col) = w;
;             }
;         }
	v_rcp_f32_e32 v154, v154
	v_rcp_f32_e32 v155, v155
	s_nop 0
	v_pk_mul_f32 v[152:153], v[72:73], v[152:153]
	v_pk_mul_f32 v[154:155], v[74:75], v[154:155]
	v_pk_mul_f32 v[152:153], v[76:77], v[152:153]
	v_pk_mul_f32 v[154:155], v[78:79], v[154:155]
	v_cvt_pk_bf16_f32 v152, v152, v153
	v_cvt_pk_bf16_f32 v153, v154, v155
	v_mul_f32_e32 v156, 0xbfb8aa3b, v80
	v_mul_f32_e32 v157, 0xbfb8aa3b, v81
	v_mul_f32_e32 v158, 0xbfb8aa3b, v82
	v_mul_f32_e32 v159, 0xbfb8aa3b, v83
	v_exp_f32_e32 v156, v156
	v_exp_f32_e32 v157, v157
	v_exp_f32_e32 v158, v158
	v_exp_f32_e32 v159, v159
	s_nop 0
	v_add_f32_e32 v156, 1.0, v156
	v_add_f32_e32 v157, 1.0, v157
	v_add_f32_e32 v158, 1.0, v158
	v_add_f32_e32 v159, 1.0, v159
	v_rcp_f32_e32 v156, v156
	v_rcp_f32_e32 v157, v157
	v_rcp_f32_e32 v158, v158
	v_rcp_f32_e32 v159, v159
	s_nop 0
	v_pk_mul_f32 v[156:157], v[80:81], v[156:157]
	v_pk_mul_f32 v[158:159], v[82:83], v[158:159]
	v_pk_mul_f32 v[156:157], v[84:85], v[156:157]
	v_pk_mul_f32 v[158:159], v[86:87], v[158:159]
	v_cvt_pk_bf16_f32 v154, v156, v157
	v_cvt_pk_bf16_f32 v155, v158, v159
	s_nop 1
	v_permlane16_swap_b32_e32 v152, v154
	v_permlane16_swap_b32_e32 v153, v155
	global_store_dwordx4 v237, v[152:155], s[2:3] offset:128
	s_add_u32 s2, s2, 0x84000
	s_addc_u32 s3, s3, 0
	v_mul_f32_e32 v160, 0xbfb8aa3b, v88
	v_mul_f32_e32 v161, 0xbfb8aa3b, v89
	v_mul_f32_e32 v162, 0xbfb8aa3b, v90
	v_mul_f32_e32 v163, 0xbfb8aa3b, v91
	v_exp_f32_e32 v160, v160
	v_exp_f32_e32 v161, v161
	v_exp_f32_e32 v162, v162
	v_exp_f32_e32 v163, v163
	s_nop 0
	v_add_f32_e32 v160, 1.0, v160
	v_add_f32_e32 v161, 1.0, v161
	v_add_f32_e32 v162, 1.0, v162
	v_add_f32_e32 v163, 1.0, v163
	v_rcp_f32_e32 v160, v160
	v_rcp_f32_e32 v161, v161
	v_rcp_f32_e32 v162, v162
	v_rcp_f32_e32 v163, v163
	s_nop 0
	v_pk_mul_f32 v[160:161], v[88:89], v[160:161]
	v_pk_mul_f32 v[162:163], v[90:91], v[162:163]
	v_pk_mul_f32 v[160:161], v[92:93], v[160:161]
	v_pk_mul_f32 v[162:163], v[94:95], v[162:163]
	v_cvt_pk_bf16_f32 v160, v160, v161
	v_cvt_pk_bf16_f32 v161, v162, v163
	v_mul_f32_e32 v164, 0xbfb8aa3b, v96
	v_mul_f32_e32 v165, 0xbfb8aa3b, v97
	v_mul_f32_e32 v166, 0xbfb8aa3b, v98
	v_mul_f32_e32 v167, 0xbfb8aa3b, v99
	v_exp_f32_e32 v164, v164
	v_exp_f32_e32 v165, v165
	v_exp_f32_e32 v166, v166
	v_exp_f32_e32 v167, v167
	s_nop 0
	v_add_f32_e32 v164, 1.0, v164
	v_add_f32_e32 v165, 1.0, v165
	v_add_f32_e32 v166, 1.0, v166
	v_add_f32_e32 v167, 1.0, v167
	v_rcp_f32_e32 v164, v164
	v_rcp_f32_e32 v165, v165
	v_rcp_f32_e32 v166, v166
	v_rcp_f32_e32 v167, v167
	s_nop 0
	v_pk_mul_f32 v[164:165], v[96:97], v[164:165]
	v_pk_mul_f32 v[166:167], v[98:99], v[166:167]
	v_pk_mul_f32 v[164:165], v[100:101], v[164:165]
	v_pk_mul_f32 v[166:167], v[102:103], v[166:167]
	v_cvt_pk_bf16_f32 v162, v164, v165
	v_cvt_pk_bf16_f32 v163, v166, v167
	s_nop 1
	v_permlane16_swap_b32_e32 v160, v162
	v_permlane16_swap_b32_e32 v161, v163
	global_store_dwordx4 v237, v[160:163], s[2:3] offset:0
	v_mul_f32_e32 v168, 0xbfb8aa3b, v120
	v_mul_f32_e32 v169, 0xbfb8aa3b, v121
	v_mul_f32_e32 v170, 0xbfb8aa3b, v122
	v_mul_f32_e32 v171, 0xbfb8aa3b, v123
	v_exp_f32_e32 v168, v168
	v_exp_f32_e32 v169, v169
	v_exp_f32_e32 v170, v170
	v_exp_f32_e32 v171, v171
	s_nop 0
	v_add_f32_e32 v168, 1.0, v168
	v_add_f32_e32 v169, 1.0, v169
	v_add_f32_e32 v170, 1.0, v170
	v_add_f32_e32 v171, 1.0, v171
	v_rcp_f32_e32 v168, v168
	v_rcp_f32_e32 v169, v169
	v_rcp_f32_e32 v170, v170
	v_rcp_f32_e32 v171, v171
	s_nop 0
	v_pk_mul_f32 v[168:169], v[120:121], v[168:169]
	v_pk_mul_f32 v[170:171], v[122:123], v[170:171]
	v_pk_mul_f32 v[168:169], v[124:125], v[168:169]
	v_pk_mul_f32 v[170:171], v[126:127], v[170:171]
	v_cvt_pk_bf16_f32 v168, v168, v169
	v_cvt_pk_bf16_f32 v169, v170, v171
	v_mul_f32_e32 v172, 0xbfb8aa3b, v128
	v_mul_f32_e32 v173, 0xbfb8aa3b, v129
	v_mul_f32_e32 v174, 0xbfb8aa3b, v130
	v_mul_f32_e32 v175, 0xbfb8aa3b, v131
	v_exp_f32_e32 v172, v172
	v_exp_f32_e32 v173, v173
	v_exp_f32_e32 v174, v174
	v_exp_f32_e32 v175, v175
	s_nop 0
	v_add_f32_e32 v172, 1.0, v172
	v_add_f32_e32 v173, 1.0, v173
	v_add_f32_e32 v174, 1.0, v174
	v_add_f32_e32 v175, 1.0, v175
; DI unsigned pk2(float lo, float hi) { const f32x2 v = {lo, hi}; return __builtin_bit_cast(unsigned, __builtin_convertvector(v, bf2_t)); }
; DI void gemm_gu(const Params& p, size_t woff, int bid, int nb, char* smem, const int tid) {
;     ...
;         const int nb0 = n0 + wn * 64;
; #pragma unroll
;         for (int mi = 0; mi < 4; ++mi) {
;             const int row = m0 + wm * 64 + mi * 16 + r;
; #pragma unroll
;             for (int pr = 0; pr < 2; ++pr) {
;                 const f32x4 g = acc[mi][2 * pr], u = acc[mi][2 * pr + 1];
;                 float o[4];
; #pragma unroll
;                 for (int j = 0; j < 4; ++j) o[j] = g[j] * __builtin_amdgcn_rcpf(1.0f + __builtin_amdgcn_exp2f(-LOG2E * g[j])) * u[j];
;                 const int col = ((nb0 + pr * 32) >> 5) * 16 + q * 4;
;                 u32x2 w; w.x = pk2(o[0], o[1]); w.y = pk2(o[2], o[3]);
;                 *(u32x2*)(ACT + (size_t)row * DFF + col) = w;
;             }
;         }
	v_rcp_f32_e32 v172, v172
	v_rcp_f32_e32 v173, v173
	v_rcp_f32_e32 v174, v174
	v_rcp_f32_e32 v175, v175
	s_nop 0
	v_pk_mul_f32 v[172:173], v[128:129], v[172:173]
	v_pk_mul_f32 v[174:175], v[130:131], v[174:175]
	v_pk_mul_f32 v[172:173], v[132:133], v[172:173]
	v_pk_mul_f32 v[174:175], v[134:135], v[174:175]
	v_cvt_pk_bf16_f32 v170, v172, v173
	v_cvt_pk_bf16_f32 v171, v174, v175
	s_nop 1
	v_permlane16_swap_b32_e32 v168, v170
	v_permlane16_swap_b32_e32 v169, v171
	global_store_dwordx4 v237, v[168:171], s[2:3] offset:128
	s_add_u32 s2, s2, 0x2c000
	s_addc_u32 s3, s3, 0
	v_mul_f32_e32 v152, 0xbfb8aa3b, v104
	v_mul_f32_e32 v153, 0xbfb8aa3b, v105
	v_mul_f32_e32 v154, 0xbfb8aa3b, v106
	v_mul_f32_e32 v155, 0xbfb8aa3b, v107
	v_exp_f32_e32 v152, v152
	v_exp_f32_e32 v153, v153
	v_exp_f32_e32 v154, v154
	v_exp_f32_e32 v155, v155
	s_nop 0
	v_add_f32_e32 v152, 1.0, v152
	v_add_f32_e32 v153, 1.0, v153
	v_add_f32_e32 v154, 1.0, v154
	v_add_f32_e32 v155, 1.0, v155
	v_rcp_f32_e32 v152, v152
	v_rcp_f32_e32 v153, v153
	v_rcp_f32_e32 v154, v154
	v_rcp_f32_e32 v155, v155
	s_nop 0
	v_pk_mul_f32 v[152:153], v[104:105], v[152:153]
	v_pk_mul_f32 v[154:155], v[106:107], v[154:155]
	v_pk_mul_f32 v[152:153], v[108:109], v[152:153]
	v_pk_mul_f32 v[154:155], v[110:111], v[154:155]
	v_cvt_pk_bf16_f32 v152, v152, v153
	v_cvt_pk_bf16_f32 v153, v154, v155
	v_mul_f32_e32 v156, 0xbfb8aa3b, v112
	v_mul_f32_e32 v157, 0xbfb8aa3b, v113
	v_mul_f32_e32 v158, 0xbfb8aa3b, v114
	v_mul_f32_e32 v159, 0xbfb8aa3b, v115
	v_exp_f32_e32 v156, v156
	v_exp_f32_e32 v157, v157
	v_exp_f32_e32 v158, v158
	v_exp_f32_e32 v159, v159
	s_nop 0
	v_add_f32_e32 v156, 1.0, v156
	v_add_f32_e32 v157, 1.0, v157
	v_add_f32_e32 v158, 1.0, v158
	v_add_f32_e32 v159, 1.0, v159
	v_rcp_f32_e32 v156, v156
	v_rcp_f32_e32 v157, v157
	v_rcp_f32_e32 v158, v158
	v_rcp_f32_e32 v159, v159
	s_nop 0
	v_pk_mul_f32 v[156:157], v[112:113], v[156:157]
	v_pk_mul_f32 v[158:159], v[114:115], v[158:159]
	v_pk_mul_f32 v[156:157], v[116:117], v[156:157]
	v_pk_mul_f32 v[158:159], v[118:119], v[158:159]
	v_cvt_pk_bf16_f32 v154, v156, v157
	v_cvt_pk_bf16_f32 v155, v158, v159
	s_nop 1
	v_permlane16_swap_b32_e32 v152, v154
	v_permlane16_swap_b32_e32 v153, v155
	global_store_dwordx4 v237, v[152:155], s[2:3] offset:0
	v_mul_f32_e32 v160, 0xbfb8aa3b, v136
	v_mul_f32_e32 v161, 0xbfb8aa3b, v137
	v_mul_f32_e32 v162, 0xbfb8aa3b, v138
	v_mul_f32_e32 v163, 0xbfb8aa3b, v139
	v_exp_f32_e32 v160, v160
	v_exp_f32_e32 v161, v161
	v_exp_f32_e32 v162, v162
	v_exp_f32_e32 v163, v163
	s_nop 0
	v_add_f32_e32 v160, 1.0, v160
	v_add_f32_e32 v161, 1.0, v161
	v_add_f32_e32 v162, 1.0, v162
	v_add_f32_e32 v163, 1.0, v163
	v_rcp_f32_e32 v160, v160
	v_rcp_f32_e32 v161, v161
	v_rcp_f32_e32 v162, v162
	v_rcp_f32_e32 v163, v163
	s_nop 0
	v_pk_mul_f32 v[160:161], v[136:137], v[160:161]
	v_pk_mul_f32 v[162:163], v[138:139], v[162:163]
	v_pk_mul_f32 v[160:161], v[140:141], v[160:161]
	v_pk_mul_f32 v[162:163], v[142:143], v[162:163]
	v_cvt_pk_bf16_f32 v160, v160, v161
	v_cvt_pk_bf16_f32 v161, v162, v163
	v_mul_f32_e32 v164, 0xbfb8aa3b, v144
	v_mul_f32_e32 v165, 0xbfb8aa3b, v145
	v_mul_f32_e32 v166, 0xbfb8aa3b, v146
	v_mul_f32_e32 v167, 0xbfb8aa3b, v147
	v_exp_f32_e32 v164, v164
	v_exp_f32_e32 v165, v165
	v_exp_f32_e32 v166, v166
	v_exp_f32_e32 v167, v167
	s_nop 0
	v_add_f32_e32 v164, 1.0, v164
	v_add_f32_e32 v165, 1.0, v165
	v_add_f32_e32 v166, 1.0, v166
	v_add_f32_e32 v167, 1.0, v167
	v_rcp_f32_e32 v164, v164
	v_rcp_f32_e32 v165, v165
	v_rcp_f32_e32 v166, v166
	v_rcp_f32_e32 v167, v167
	s_nop 0
	v_pk_mul_f32 v[164:165], v[144:145], v[164:165]
	v_pk_mul_f32 v[166:167], v[146:147], v[166:167]
	v_pk_mul_f32 v[164:165], v[148:149], v[164:165]
	v_pk_mul_f32 v[166:167], v[150:151], v[166:167]
	v_cvt_pk_bf16_f32 v162, v164, v165
	v_cvt_pk_bf16_f32 v163, v166, v167
	s_nop 1
	v_permlane16_swap_b32_e32 v160, v162
	v_permlane16_swap_b32_e32 v161, v163
	global_store_dwordx4 v237, v[160:163], s[2:3] offset:128
	s_cmp_eq_u32 s54, 0
	s_cbranch_scc1 .LBB0_860
	s_mov_b32 s51, s76
	s_mov_b32 s57, s59
	s_mov_b32 s58, s60
	s_branch .Lgu_tile
